# windowed attention phase: one static s_setprio 1 for waves 4-7 (younger half), reset at phase end
# speedup vs baseline: 1.0024x; 1.0024x over previous
; DI void win_mfma_phase(const Args& A, int wave_s, int l, bool need_ctx, LAS unsigned char* lds) {
;     const Ctx C = make_ctx(A, wave_s);
;     const int lane = C.lane, wave = C.wave, r = lane & 31, h = lane >> 5;
;     const float Mb2 = 8.f * 1.4426950408889634f * wave_max(C.lane, fabsf(C.wqg[l * 64 + lane])) * wave_max(C.lane, fabsf(C.wkg[l * 64 + lane]));
;     const int nunits = 1024 + (need_ctx ? 32 : 0);
;     const int srow = C.tid >> 3, sch = C.tid & 7;
;     const int q4 = (lane & 15) >> 2, p4 = lane & 3, grp = (lane >> 4) & 1;
;     const int voff = (4 * h + q4) * KV_PITCH + (16 * grp + 4 * p4) * 2;
;     const int g = wave >> 1, qh = wave & 1;
;     for (int u = blockIdx.x; u < nunits; u += gridDim.x) {
;         int b, kv, qrow0, t0, ntiles, tfirst;
;         bool lat;
;         if (u < 1024) { lat = true; b = u >> 8; kv = (u >> 7) & 1; t0 = (u & 127) * 64; qrow0 = b * LSEQ + t0; }
;         else { lat = false; const int uu = u - 1024; b = uu >> 3; kv = (uu >> 2) & 1; t0 = (uu & 3) * 64; qrow0 = NLAT + b * LCTX + t0; }
;         const int ilo = lat ? (t0 >= 128 ? 0 : (t0 >= 64 ? 1 : 2)) : 5, ihi = lat ? (t0 + 128 < LSEQ ? 4 : (t0 + 64 < LSEQ ? 3 : 2)) : 4;
;         const int nloc = lat ? (ihi - ilo + 1) : 0;
;         ntiles = nloc + 4; tfirst = ilo;
;         const int head = kv * 4 + g;
;         const int tq = t0 + qh * 32 + r;
;         const bf16* qp = C.P + (size_t)(qrow0 + qh * 32 + r) * INW + CA_Q + head * 64;
;         bf16x8 Qf[4];
; #pragma unroll
;         for (int s = 0; s < 4; ++s) Qf[s] = *(const bf16x8*)(qp + s * 16 + h * 8);
;         f32x16 O[2];
; #pragma unroll
;         for (int mt = 0; mt < 2; ++mt)
; #pragma unroll
;             for (int i = 0; i < 16; ++i) O[mt][i] = 0.f;
;         float ls = 0.f;
;         v4u kreg, vreg, kreg2, vreg2;
;         auto tile_row = [&](int it) -> int { return it < nloc ? b * LSEQ + t0 + 64 * (tfirst + it - 2) : NLAT + b * LCTX + 64 * (it - nloc); };
;         { const bf16* kr = C.P + (size_t)(tile_row(0) + srow) * INW; kreg = *(const v4u*)(kr + CA_K + kv * 64 + sch * 8); vreg = *(const v4u*)(kr + CA_V + kv * 64 + sch * 8); }
;         { const bf16* kr = C.P + (size_t)(tile_row(1) + srow) * INW; kreg2 = *(const v4u*)(kr + CA_K + kv * 64 + sch * 8); vreg2 = *(const v4u*)(kr + CA_V + kv * 64 + sch * 8); }
;         __syncthreads();
.LBB0_304:
	s_or_b64 exec, exec, s[4:5]
	s_bitcmp1_b32 s94, 8
	s_cbranch_scc0 .Lprio_win_skip
	s_setprio 1
.Lprio_win_skip:
	v_mbcnt_lo_u32_b32 v0, -1, 0
	v_mbcnt_hi_u32_b32 v0, -1, v0
	v_readlane_b32 s4, v252, 1
	v_add_u32_e32 v2, s42, v0
	v_ashrrev_i32_e32 v3, 31, v2
	v_lshlrev_b64 v[4:5], 2, v[2:3]
	v_readlane_b32 s6, v252, 3
	v_readlane_b32 s7, v252, 4
	v_readlane_b32 s8, v252, 5
	v_readlane_b32 s9, v252, 6
	v_lshl_add_u64 v[2:3], s[6:7], 0, v[4:5]
	global_load_dword v2, v[2:3], off
	v_lshl_add_u64 v[4:5], s[8:9], 0, v[4:5]
	global_load_dword v4, v[4:5], off
	v_lshlrev_b32_e32 v1, 2, v0
	v_xor_b32_e32 v6, 4, v1
	v_xor_b32_e32 v7, 8, v1
	v_xor_b32_e32 v8, 16, v1
	v_xor_b32_e32 v9, 32, v1
	v_xor_b32_e32 v10, 64, v1
	v_xor_b32_e32 v117, 0x80, v1
	v_readlane_b32 s5, v252, 2
	s_and_b64 s[4:5], s[58:59], exec
	s_movk_i32 s2, 0x420
	s_cselect_b32 s2, s2, 0x400
	s_cmp_ge_i32 s65, s2
	v_readlane_b32 s10, v252, 7
	v_readlane_b32 s11, v252, 8
	v_readlane_b32 s12, v252, 9
	v_readlane_b32 s13, v252, 10
	v_readlane_b32 s14, v252, 11
	v_readlane_b32 s15, v252, 12
	v_readlane_b32 s16, v252, 13
	v_readlane_b32 s17, v252, 14
	v_readlane_b32 s18, v252, 15
	v_readlane_b32 s19, v252, 16
	s_waitcnt vmcnt(1)
	v_and_b32_e32 v3, 0x7fffffff, v2
	ds_bpermute_b32 v3, v6, v3
	s_waitcnt vmcnt(0)
	v_and_b32_e32 v5, 0x7fffffff, v4
	ds_bpermute_b32 v5, v6, v5
	v_max_f32_e64 v2, |v2|, |v2|
	v_max_f32_e64 v4, |v4|, |v4|
	s_waitcnt lgkmcnt(1)
	v_max_f32_e32 v3, v3, v3
	v_max_f32_e32 v2, v2, v3
	s_waitcnt lgkmcnt(0)
	v_max_f32_e32 v5, v5, v5
	v_max_f32_e32 v4, v4, v5
	ds_bpermute_b32 v3, v7, v2
	ds_bpermute_b32 v5, v7, v4
	s_waitcnt lgkmcnt(1)
	v_max_f32_e32 v3, v3, v3
	s_waitcnt lgkmcnt(0)
	v_max_f32_e32 v5, v5, v5
	v_max_f32_e32 v2, v2, v3
	v_max_f32_e32 v4, v4, v5
	ds_bpermute_b32 v3, v8, v2
	ds_bpermute_b32 v5, v8, v4
	s_waitcnt lgkmcnt(1)
	v_max_f32_e32 v3, v3, v3
	s_waitcnt lgkmcnt(0)
	v_max_f32_e32 v5, v5, v5
	v_max_f32_e32 v2, v2, v3
	v_max_f32_e32 v4, v4, v5
	ds_bpermute_b32 v3, v9, v2
	ds_bpermute_b32 v5, v9, v4
	s_waitcnt lgkmcnt(1)
	v_max_f32_e32 v3, v3, v3
	s_waitcnt lgkmcnt(0)
	v_max_f32_e32 v5, v5, v5
	v_max_f32_e32 v2, v2, v3
	v_max_f32_e32 v4, v4, v5
	ds_bpermute_b32 v3, v10, v2
	ds_bpermute_b32 v5, v10, v4
	s_waitcnt lgkmcnt(1)
	v_max_f32_e32 v3, v3, v3
	s_waitcnt lgkmcnt(0)
	v_max_f32_e32 v5, v5, v5
	v_max_f32_e32 v2, v2, v3
	v_max_f32_e32 v4, v4, v5
	ds_bpermute_b32 v3, v117, v2
	ds_bpermute_b32 v5, v117, v4
	s_cbranch_scc1 .LBB0_325
	s_waitcnt lgkmcnt(1)
	v_max_f32_e32 v3, v3, v3
	v_max_f32_e32 v2, v2, v2
	v_max_f32_e32 v2, v2, v3
	s_waitcnt lgkmcnt(0)
	v_max_f32_e32 v3, v5, v5
	v_max_f32_e32 v4, v4, v4
	v_ashrrev_i32_e32 v7, 5, v0
	v_mul_f32_e32 v2, 0x4138aa3b, v2
	v_max_f32_e32 v3, v4, v3
	v_add_u32_e32 v6, s94, v0
	v_mul_f32_e32 v124, v2, v3
	v_lshrrev_b32_e32 v2, 2, v0
	v_and_b32_e32 v3, 16, v0
	v_lshlrev_b32_e32 v112, 2, v7
	v_ashrrev_i32_e32 v125, 3, v6
	v_and_or_b32 v2, v2, 3, v112
	s_movk_i32 s5, 0x90
	v_and_or_b32 v1, v1, 12, v3
	v_and_b32_e32 v3, 31, v0
	v_and_b32_e32 v0, 7, v0
	v_readlane_b32 s4, v254, 55
	v_mul_lo_u32 v2, v2, s5
	v_lshlrev_b32_e32 v1, 1, v1
	v_or_b32_e32 v126, s4, v3
	v_mul_lo_u32 v4, v125, s5
	v_lshlrev_b32_e32 v160, 4, v0
	v_readlane_b32 s4, v254, 56
	v_lshlrev_b32_e32 v114, 3, v7
	v_lshlrev_b32_e32 v116, 3, v0
	v_add3_u32 v127, 0, v4, v160
	v_xor_b32_e32 v0, 0x80000000, v124
	v_lshlrev_b32_e32 v4, 4, v7
	v_mul_u32_u24_e32 v5, 0x90, v3
	v_add3_u32 v129, v2, v1, 0
	v_add_u32_e32 v1, s4, v3
	v_ashrrev_i32_e32 v115, 31, v114
	s_lshl_b32 s8, s56, 3
	v_mov_b32_e32 v16, v0
	v_mov_b32_e32 v17, v0
	v_mov_b32_e32 v18, v0
	v_mov_b32_e32 v19, v0
	v_mov_b32_e32 v20, v0
	v_mov_b32_e32 v21, v0
	v_mov_b32_e32 v22, v0
	v_mov_b32_e32 v23, v0
	v_mov_b32_e32 v24, v0
	v_mov_b32_e32 v25, v0
	v_mov_b32_e32 v26, v0
	v_mov_b32_e32 v27, v0
	v_mov_b32_e32 v28, v0
	v_mov_b32_e32 v29, v0
	v_mov_b32_e32 v30, v0
	v_mov_b32_e32 v31, v0
	v_ashrrev_i32_e32 v113, 31, v112
	v_add3_u32 v128, 0, v4, v5
	v_lshl_add_u64 v[118:119], s[84:85], 0, v[160:161]
	v_sub_u32_e32 v130, v1, v112
	s_mov_b32 s9, s65
	s_branch .LBB0_307

; __device__ __forceinline__ void xcd_barrier(const XcdBarrier& b, int xtid) {
;     asm volatile("s_waitcnt vmcnt(0)" ::: "memory");
;     __syncthreads();
;     if (xtid == 0) {
;         unsigned* bar = b.bar; unsigned bx_ = b.x; asm volatile("" : "+s"(bx_));
;         __builtin_amdgcn_s_waitcnt(0);
;         unsigned nloc = b.st[0], nx = b.st[1];
;         if (nloc == 0u) { xcd_barrier_complete(bar, bx_, nloc, nx); b.st[0] = nloc; b.st[1] = nx; }
.LBB0_325:
	s_setprio 0
	v_mbcnt_lo_u32_b32 v0, -1, 0
	v_mbcnt_hi_u32_b32 v0, -1, v0
	s_waitcnt vmcnt(0)
	s_waitcnt lgkmcnt(0)
	v_sub_u32_e32 v0, 0, v0
	v_cmp_eq_u32_e32 vcc, s94, v0
	s_barrier
	s_and_saveexec_b64 s[4:5], vcc
	s_cbranch_execz .LBB0_377
	v_readlane_b32 s6, v254, 62
	s_mov_b32 s2, s64
	s_waitcnt vmcnt(0) expcnt(0) lgkmcnt(0)
	v_mov_b32_e32 v0, s6
	ds_read_b32 v2, v0
	v_readlane_b32 s6, v254, 63
	s_waitcnt lgkmcnt(0)
	v_cmp_ne_u32_e32 vcc, 0, v2
	v_mov_b32_e32 v0, s6
	ds_read_b32 v0, v0
	s_cbranch_vccnz .LBB0_341
	s_mov_b32 s12, 1
	s_branch .LBB0_329
